# P0 rope cos/sin table: 4 position loads in flight per thread instead of a load-wait-store chain per entry
# speedup vs baseline: 1.0335x; 1.0002x over previous
; __device__ __forceinline__ void p0_prologue(const Params& P, LAS unsigned char* lds, int G) {
;     ...
;     for (int idx = blockIdx.x * NTHREADS + tid; idx < M * 32; idx += G * NTHREADS) {
;         const int m = idx >> 5, i = idx & 31; const double rev = (double)P.pos[m] * INVF_REV[i]; const float fr = (float)(rev - floor(rev));
;         cs[2 * idx] = __builtin_amdgcn_cosf(fr); cs[2 * idx + 1] = __builtin_amdgcn_sinf(fr);
;     }
.LBB0_89:
	s_or_b64 exec, exec, s[4:5]
	s_add_u32 s54, s58, 0x300000
	s_addc_u32 s55, s59, 0
	s_lshl_b32 s43, s2, 9
	v_add_u32_e32 v6, s43, v1
	s_mov_b32 s4, 0x80000
	s_lshl_b32 s33, s92, 9
	v_cmp_gt_i32_e32 vcc, s4, v6
	s_and_saveexec_b64 s[4:5], vcc
	s_cbranch_execz .LBB0_92
	v_and_b32_e32 v2, 31, v1
	v_lshlrev_b32_e32 v2, 3, v2
	s_getpc_b64 s[8:9]
	s_add_u32 s8, s8, _ZL8INVF_REV@rel32@lo+4
	s_addc_u32 s9, s9, _ZL8INVF_REV@rel32@hi+12
	global_load_dwordx2 v[2:3], v2, s[8:9]
	v_lshlrev_b32_e32 v1, 1, v1
	v_lshl_add_u32 v4, s2, 10, v1
	s_lshl_b32 s10, s92, 10
	s_mov_b64 s[8:9], 0
	s_mov_b32 s11, 0x7ffff
	s_cmpk_lg_u32 s92, 0x100
	s_cbranch_scc1 .LBB0_91
	v_ashrrev_i32_e32 v8, 5, v6
	s_add_u32 s12, s64, 0x4000
	s_addc_u32 s13, s65, 0
	v_lshlrev_b32_e32 v8, 2, v8
	s_add_u32 s14, s64, 0x8000
	s_addc_u32 s15, s65, 0
	s_add_u32 s16, s64, 0xc000
	s_addc_u32 s17, s65, 0
	s_waitcnt lgkmcnt(0)
	global_load_dword v20, v8, s[64:65]
	global_load_dword v21, v8, s[12:13]
	global_load_dword v22, v8, s[14:15]
	global_load_dword v23, v8, s[16:17]
	v_lshlrev_b32_e32 v9, 2, v4
	s_waitcnt vmcnt(3)
	v_cvt_f64_i32_e32 v[10:11], v20
	v_mul_f64 v[12:13], v[2:3], v[10:11]
	v_floor_f64_e32 v[12:13], v[12:13]
	v_fma_f64 v[10:11], v[2:3], v[10:11], -v[12:13]
	v_cvt_f32_f64_e32 v1, v[10:11]
	s_add_u32 s12, s54, 0x0
	s_addc_u32 s13, s55, 0
	v_cos_f32_e32 v10, v1
	v_sin_f32_e32 v11, v1
	global_store_dwordx2 v9, v[10:11], s[12:13]
	s_waitcnt vmcnt(3)
	v_cvt_f64_i32_e32 v[10:11], v21
	v_mul_f64 v[12:13], v[2:3], v[10:11]
	v_floor_f64_e32 v[12:13], v[12:13]
	v_fma_f64 v[10:11], v[2:3], v[10:11], -v[12:13]
	v_cvt_f32_f64_e32 v1, v[10:11]
	s_add_u32 s12, s54, 0x100000
	s_addc_u32 s13, s55, 0
	v_cos_f32_e32 v10, v1
	v_sin_f32_e32 v11, v1
	global_store_dwordx2 v9, v[10:11], s[12:13]
	s_waitcnt vmcnt(3)
	v_cvt_f64_i32_e32 v[10:11], v22
	v_mul_f64 v[12:13], v[2:3], v[10:11]
	v_floor_f64_e32 v[12:13], v[12:13]
	v_fma_f64 v[10:11], v[2:3], v[10:11], -v[12:13]
	v_cvt_f32_f64_e32 v1, v[10:11]
	s_add_u32 s12, s54, 0x200000
	s_addc_u32 s13, s55, 0
	v_cos_f32_e32 v10, v1
	v_sin_f32_e32 v11, v1
	global_store_dwordx2 v9, v[10:11], s[12:13]
	s_waitcnt vmcnt(3)
	v_cvt_f64_i32_e32 v[10:11], v23
	v_mul_f64 v[12:13], v[2:3], v[10:11]
	v_floor_f64_e32 v[12:13], v[12:13]
	v_fma_f64 v[10:11], v[2:3], v[10:11], -v[12:13]
	v_cvt_f32_f64_e32 v1, v[10:11]
	s_add_u32 s12, s54, 0x300000
	s_addc_u32 s13, s55, 0
	v_cos_f32_e32 v10, v1
	v_sin_f32_e32 v11, v1
	global_store_dwordx2 v9, v[10:11], s[12:13]
	s_branch .LBB0_92
